# DSA: next item indexer-q fragments loaded one item ahead into free VGPRs (on top of v13)
# baseline (speedup 1.0000x reference)
; template <bool DUMMY> __device__ __forceinline__ void phase_dsa(const Args& a, unsigned char* lds) {
;     ...
;     if ((int)blockIdx.x < 16384) DSA_LOAD_ITEM(blockIdx.x);
;     ...
;         bf16x8 af[2][2];
; #pragma unroll
;         for (int T = 0; T < 2; ++T)
; #pragma unroll
;             for (int ks = 0; ks < 2; ++ks) af[T][ks] = *(const bf16x8*)(P + (r0 + (l15 >> 2)) * LDP + C_IQ + (4 * T + (l15 & 3)) * 64 + ks * 32 + quad * 8);
.LBB0_855:
	s_cmpk_lt_i32 s2, 0x4000
	s_cselect_b64 s[0:1], -1, 0
	s_cmpk_gt_i32 s2, 0x3fff
	s_cbranch_scc1 .LBB0_857
	s_lshr_b32 s4, s2, 1
	s_lshl_b32 s5, s2, 13
	s_and_b32 s4, s4, 0x7ffffffc
	s_and_b32 s5, s5, 0xe000
	v_mov_b32_e32 v14, v156
	s_add_i32 s4, s5, s4
	v_mov_b32_e32 v9, 0
	v_bfe_u32 v76, v14, 2, 2
	v_or_b32_e32 v76, s4, v76
	s_movk_i32 s98, 0x2800
	v_mov_b64_e32 v[78:79], s[44:45]
	v_mad_i64_i32 v[78:79], s[100:101], v76, s98, v[78:79]
	v_and_b32_e32 v80, 48, v14
	v_mov_b32_e32 v81, 0
	v_lshl_add_u64 v[78:79], v[78:79], 0, v[80:81]
	v_lshlrev_b32_e32 v80, 7, v14
	v_and_b32_e32 v80, 0x180, v80
	v_lshl_add_u64 v[78:79], v[78:79], 0, v[80:81]
	global_load_dwordx4 v[60:63], v[78:79], off offset:1536
	global_load_dwordx4 v[64:67], v[78:79], off offset:1600
	global_load_dwordx4 v[68:71], v[78:79], off offset:2048
	global_load_dwordx4 v[72:75], v[78:79], off offset:2112
	v_lshrrev_b32_e32 v0, 4, v14
	v_and_or_b32 v8, v0, 3, s4
	v_lshlrev_b64 v[0:1], 6, v[8:9]
	v_lshl_add_u64 v[10:11], s[58:59], 0, v[0:1]
	global_load_dwordx4 v[0:3], v[10:11], off offset:16
	global_load_dwordx4 v[4:7], v[10:11], off
	v_lshlrev_b32_e32 v8, 2, v14
	v_ashrrev_i32_e32 v10, 8, v14
	s_mov_b32 s5, 0
	v_and_b32_e32 v8, 0x3fc, v8
	v_ashrrev_i32_e32 v11, 31, v10
	v_lshl_add_u64 v[8:9], s[44:45], 0, v[8:9]
	v_lshl_add_u64 v[10:11], v[10:11], 0, s[4:5]
	s_movk_i32 s8, 0x2800
	v_mad_u64_u32 v[12:13], s[6:7], v10, s8, v[8:9]
	v_add_u32_e32 v10, 0x200, v14
	v_ashrrev_i32_e32 v10, 8, v10
	v_mad_i32_i24 v13, v11, s8, v13
	v_ashrrev_i32_e32 v11, 31, v10
	v_lshl_add_u64 v[10:11], v[10:11], 0, s[4:5]
	v_mad_u64_u32 v[8:9], s[4:5], v10, s8, v[8:9]
	v_mad_i32_i24 v9, v11, s8, v9
	global_load_dword v220, v[12:13], off
	global_load_dword v221, v[8:9], off
	s_andn2_b64 vcc, exec, s[0:1]
	s_cbranch_vccz .LBB0_858
	s_branch .LBB0_1299

; template <bool DUMMY> __device__ __forceinline__ void phase_dsa(const Args& a, unsigned char* lds) {
;     ...
;     if ((int)blockIdx.x < 16384) DSA_LOAD_ITEM(blockIdx.x);
;     for (int item = blockIdx.x; item < 16384; item += gridDim.x) {
;         int tid_ = threadIdx.x; asm volatile("" : "+v"(tid_));
;         const int tid = tid_, wave = __builtin_amdgcn_readfirstlane(tid >> 6), lane = tid & 63, quad = lane >> 4, l15 = lane & 15;
;         const int b = item & 7, tq = item >> 3, t0 = tq * 4, L = ((t0 >> 6) + 1) * 64;
;         const size_t r0 = (size_t)b * SEQ + t0;
.LBB0_858:
	s_mov_b32 s4, 0
	s_mov_b32 s6, s4
	s_mov_b32 s7, s4
	s_add_u32 s19, s70, 0x34800000
	s_mov_b32 s5, s4
	v_mov_b64_e32 v[248:249], s[6:7]
	v_mov_b32_e32 v9, 0
	v_mbcnt_hi_u32_b32 v218, -1, v157
	s_addc_u32 s36, s71, 0
	v_mov_b64_e32 v[246:247], s[4:5]
	s_add_i32 s37, 0, 0x26080
	s_movk_i32 s38, 0x2800
	s_movk_i32 s39, 0xff
	s_movk_i32 s40, 0x100
	s_mov_b32 s41, 0x8020
	s_movk_i32 s42, 0x1c1
	s_movk_i32 s43, 0x1c0
	s_movk_i32 s48, 0xbf
	v_mov_b32_e32 v159, 1
	s_mov_b32 s49, 0x7ffffeff
	v_mov_b32_e32 v216, 0x100
	s_movk_i32 s50, 0x90
	s_mov_b32 s18, 0x3e000000
	s_mov_b32 s51, 0xff800000
	v_mov_b32_e32 v217, 0x10000
	v_and_b32_e32 v219, 64, v218
	v_mov_b32_e32 v250, v9
	v_mov_b32_e32 v251, v9
	s_mov_b32 s52, s2
	s_waitcnt vmcnt(0)
	s_branch .LBB0_860

; __device__ __forceinline__ void lds_fence() { asm volatile("s_waitcnt lgkmcnt(0)" ::: "memory"); }
; #define IDX_LOAD(BUF, G) do { _Pragma("unroll") for (int tt = 0; tt < 4; ++tt) _Pragma("unroll") for (int ks = 0; ks < 2; ++ks) \
;                 BUF[tt][ks] = *(const bf16x8*)(ikb + (size_t)(((G) * 4 + tt) * 8 + ks * 4) * 128); } while (0)
; template <bool DUMMY> __device__ __forceinline__ void phase_dsa(const Args& a, unsigned char* lds) {
;     ...
;     for (int item = blockIdx.x; item < 16384; item += gridDim.x) {
;         int tid_ = threadIdx.x; asm volatile("" : "+v"(tid_));
;         const int tid = tid_, wave = __builtin_amdgcn_readfirstlane(tid >> 6), lane = tid & 63, quad = lane >> 4, l15 = lane & 15;
;         const int b = item & 7, tq = item >> 3, t0 = tq * 4, L = ((t0 >> 6) + 1) * 64;
;         const size_t r0 = (size_t)b * SEQ + t0;
;         const bool do_sel = (L > 256) && !DBG_NOSEL;
;         { u32x4* hz = (u32x4*)HIST; hz[tid] = (u32x4){0u, 0u, 0u, 0u}; hz[tid + 512] = (u32x4){0u, 0u, 0u, 0u}; }
;         if (tid < 8) CNT[4 + tid] = 0;
;         QS[tid] = qsv[0]; QS[tid + 512] = qsv[1];
;         float wq[8];
; #pragma unroll
;         for (int h = 0; h < 4; ++h) { wq[h] = wqv[0][h] * idx_scale; wq[4 + h] = wqv[1][h] * idx_scale; }
;         bf16x8 af[2][2];
; #pragma unroll
;         for (int T = 0; T < 2; ++T)
; #pragma unroll
;             for (int ks = 0; ks < 2; ++ks) af[T][ks] = *(const bf16x8*)(P + (r0 + (l15 >> 2)) * LDP + C_IQ + (4 * T + (l15 & 3)) * 64 + ks * 32 + quad * 8);
;         const int ngroups = L >> 6;
;         const bf16_t* ikb = IKC + (size_t)b * SEQ * 64 + (quad * 16 + l15) * 8;
;         bf16x8 B0[4][2], B1[4][2], B2[4][2];
;     ...
;         if (wave < ngroups) IDX_LOAD(B0, wave);
;         if (wave + 8 < ngroups) IDX_LOAD(B1, wave + 8);
;         if (wave + 16 < ngroups) IDX_LOAD(B2, wave + 16);
;         lds_fence(); __builtin_amdgcn_s_barrier();
.LBB0_860:
	s_waitcnt vmcnt(3)
	v_mov_b32_e32 v124, v156
	s_nop 0
	v_lshl_add_u32 v8, v124, 4, 0
	v_readfirstlane_b32 s62, v124
	v_add_u32_e32 v8, 0x20080, v8
	v_cmp_gt_i32_e32 vcc, 8, v124
	ds_write_b128 v8, v[246:249]
	ds_write_b128 v8, v[246:249] offset:8192
	s_and_saveexec_b64 s[0:1], vcc
	v_lshl_add_u32 v8, v124, 2, s37
	ds_write_b32 v8, v9 offset:16
	s_or_b64 exec, exec, s[0:1]
	s_ashr_i32 s22, s52, 1
	s_and_b32 s0, s22, -4
	s_andn2_b32 s22, s22, 63
	s_lshl_b32 s1, s52, 13
	s_ashr_i32 s63, s62, 6
	s_add_i32 s12, s22, 64
	s_and_b32 s64, s1, 0xe000
	s_ashr_i32 s4, s0, 31
	s_add_u32 s53, s64, s0
	v_bfe_u32 v8, v124, 2, 2
	v_or_b32_e32 v8, s53, v8
	v_mov_b64_e32 v[10:11], s[44:45]
	v_mad_i64_i32 v[10:11], s[0:1], v8, s38, v[10:11]
	v_and_b32_e32 v8, 48, v124
	v_lshl_add_u64 v[10:11], v[10:11], 0, v[8:9]
	v_lshlrev_b32_e32 v8, 7, v124
	v_and_b32_e32 v8, 0x180, v8
	v_lshl_add_u64 v[10:11], v[10:11], 0, v[8:9]
	v_mov_b64_e32 v[108:109], v[60:61]
	v_mov_b64_e32 v[110:111], v[62:63]
	v_mov_b64_e32 v[112:113], v[64:65]
	v_mov_b64_e32 v[114:115], v[66:67]
	v_mov_b64_e32 v[116:117], v[68:69]
	v_mov_b64_e32 v[118:119], v[70:71]
	v_mov_b64_e32 v[120:121], v[72:73]
	v_mov_b64_e32 v[122:123], v[74:75]
	s_addc_u32 s60, 0, s4
	v_lshl_add_u32 v8, v124, 2, 0
	s_ashr_i32 s13, s12, 6
	s_lshl_b32 s0, s64, 7
	v_add_u32_e32 v8, 0x25080, v8
	s_add_u32 s0, s56, s0
	s_waitcnt vmcnt(4)
	ds_write2st64_b32 v8, v220, v221 offset1:8
	s_addc_u32 s1, s57, 0
	v_lshlrev_b32_e32 v8, 4, v124
	v_and_b32_e32 v8, 0x3f0, v8
	s_cmp_lt_i32 s63, s13
	s_cselect_b64 s[4:5], -1, 0
	s_cmp_ge_i32 s63, s13
	v_lshl_add_u64 v[10:11], s[0:1], 0, v[8:9]
	s_cbranch_scc1 .LBB0_902
	s_lshl_b32 s0, s63, 5
	s_ashr_i32 s1, s0, 31
	s_lshl_b64 s[6:7], s[0:1], 8
	v_lshl_add_u64 v[12:13], v[10:11], 0, s[6:7]
	s_or_b32 s6, s0, 4
	s_ashr_i32 s7, s6, 31
	s_lshl_b64 s[6:7], s[6:7], 8
	v_lshl_add_u64 v[32:33], v[10:11], 0, s[6:7]
	s_or_b32 s6, s0, 8
	s_ashr_i32 s7, s6, 31
	s_lshl_b64 s[6:7], s[6:7], 8
	v_lshl_add_u64 v[52:53], v[10:11], 0, s[6:7]
	s_or_b32 s6, s0, 12
	s_ashr_i32 s7, s6, 31
	s_lshl_b64 s[6:7], s[6:7], 8
	v_lshl_add_u64 v[56:57], v[10:11], 0, s[6:7]
	s_or_b32 s6, s0, 16
	s_ashr_i32 s7, s6, 31
	s_lshl_b64 s[6:7], s[6:7], 8
	v_lshl_add_u64 v[76:77], v[10:11], 0, s[6:7]
	s_or_b32 s6, s0, 20
	s_ashr_i32 s7, s6, 31
	s_lshl_b64 s[6:7], s[6:7], 8
	v_lshl_add_u64 v[80:81], v[10:11], 0, s[6:7]
	s_or_b32 s6, s0, 24
	s_or_b32 s0, s0, 28
	s_ashr_i32 s7, s6, 31
	s_ashr_i32 s1, s0, 31
	s_lshl_b64 s[6:7], s[6:7], 8
	s_lshl_b64 s[0:1], s[0:1], 8
	v_lshl_add_u64 v[100:101], v[10:11], 0, s[6:7]
	v_lshl_add_u64 v[104:105], v[10:11], 0, s[0:1]
	global_load_dwordx4 v[12:15], v[12:13], off
	s_nop 0
	global_load_dwordx4 v[32:35], v[32:33], off
	s_nop 0
	global_load_dwordx4 v[52:55], v[52:53], off
	s_nop 0
	global_load_dwordx4 v[56:59], v[56:57], off
	s_nop 0
	global_load_dwordx4 v[76:79], v[76:77], off
	s_nop 0
	global_load_dwordx4 v[80:83], v[80:81], off
	s_nop 0
	global_load_dwordx4 v[100:103], v[100:101], off
	s_nop 0
	global_load_dwordx4 v[104:107], v[104:105], off
	s_add_i32 s0, s63, 8
	s_cmp_ge_i32 s0, s13
	s_cbranch_scc0 .LBB0_903

; __device__ __forceinline__ void lds_fence() { asm volatile("s_waitcnt lgkmcnt(0)" ::: "memory"); }
; template <bool DUMMY> __device__ __forceinline__ void phase_dsa(const Args& a, unsigned char* lds) {
;     ...
;         lds_fence(); __builtin_amdgcn_s_barrier();
;         if (item + (int)gridDim.x < 16384) DSA_LOAD_ITEM(item + (int)gridDim.x);
.LBB0_904:
	s_waitcnt lgkmcnt(0)
	s_add_i32 s52, s52, s72
	s_cmpk_gt_i32 s52, 0x3fff
	v_and_b32_e32 v222, 63, v124
	s_cselect_b64 s[20:21], -1, 0
	s_cmpk_lt_i32 s52, 0x4000
	s_barrier
	s_cbranch_scc0 .LBB0_906
	s_ashr_i32 s4, s52, 1
	s_and_b32 s4, s4, -4
	s_lshl_b32 s5, s52, 13
	s_and_b32 s5, s5, 0xe000
	s_ashr_i32 s6, s4, 31
	s_waitcnt vmcnt(2)
	v_mov_b32_e32 v112, v156
	s_add_u32 s4, s5, s4
	s_addc_u32 s5, 0, s6
	v_bfe_u32 v76, v112, 2, 2
	v_or_b32_e32 v76, s4, v76
	s_movk_i32 s98, 0x2800
	v_mov_b64_e32 v[78:79], s[44:45]
	v_mad_i64_i32 v[78:79], s[100:101], v76, s98, v[78:79]
	v_and_b32_e32 v80, 48, v112
	v_mov_b32_e32 v81, 0
	v_lshl_add_u64 v[78:79], v[78:79], 0, v[80:81]
	v_lshlrev_b32_e32 v80, 7, v112
	v_and_b32_e32 v80, 0x180, v80
	v_lshl_add_u64 v[78:79], v[78:79], 0, v[80:81]
	global_load_dwordx4 v[60:63], v[78:79], off offset:1536
	global_load_dwordx4 v[64:67], v[78:79], off offset:1600
	global_load_dwordx4 v[68:71], v[78:79], off offset:2048
	global_load_dwordx4 v[72:75], v[78:79], off offset:2112
	v_lshlrev_b32_e32 v8, 2, v112
	v_ashrrev_i32_e32 v108, 8, v112
	v_and_b32_e32 v8, 0x3fc, v8
	v_ashrrev_i32_e32 v109, 31, v108
	v_lshl_add_u64 v[10:11], s[44:45], 0, v[8:9]
	v_lshl_add_u64 v[108:109], s[4:5], 0, v[108:109]
	v_add_u32_e32 v8, 0x200, v112
	v_lshrrev_b32_e32 v0, 4, v112
	v_mad_u64_u32 v[110:111], s[6:7], v108, s38, v[10:11]
	v_ashrrev_i32_e32 v108, 8, v8
	v_and_or_b32 v0, v0, 3, s4
	v_mov_b32_e32 v1, s5
	v_mad_i32_i24 v111, v109, s38, v111
	v_ashrrev_i32_e32 v109, 31, v108
	v_lshlrev_b64 v[0:1], 6, v[0:1]
	v_lshl_add_u64 v[108:109], s[4:5], 0, v[108:109]
	v_lshl_add_u64 v[4:5], s[58:59], 0, v[0:1]
	v_mad_u64_u32 v[10:11], s[4:5], v108, s38, v[10:11]
	global_load_dwordx4 v[0:3], v[4:5], off offset:16
	s_nop 0
	global_load_dwordx4 v[4:7], v[4:5], off
	v_mad_i32_i24 v11, v109, s38, v11
	global_load_dword v220, v[110:111], off
	global_load_dword v221, v[10:11], off
